# adds E16: band attention mask compares use inline constants against (base - q) instead of 32 materialised key indices per step, stacked on E15
# speedup vs baseline: 1.0174x; 1.0012x over previous
.LBB0_637:
	s_lshl_b64 s[28:29], s[2:3], s22
	v_lshl_add_u64 v[64:65], s[28:29], 1, v[180:181]
	s_add_i32 s0, s4, s75
	s_mov_b32 s28, m0
	s_mov_b32 m0, s0
	s_nop 0
	global_load_lds_dwordx4 v[64:65], off
	s_mov_b32 m0, s28
	s_sub_i32 s28, s23, 0x80
	s_max_i32 s28, s28, 0
	s_sub_i32 s29, s76, 63
	s_cmp_le_i32 s29, s28
	s_cbranch_scc1 .Lxa_idle
	s_sub_i32 s29, s76, 0xde
	s_cmp_gt_i32 s29, s23
	s_cbranch_scc1 .Lxa_idle
	v_add_u32_e32 v164, s1, v190
	ds_read_b64_tr_b16 v[160:161], v164 offset:24576
	ds_read_b64_tr_b16 v[162:163], v164 offset:25088
	s_waitcnt lgkmcnt(9)
	v_mfma_f32_32x32x16_bf16 v[80:95], v[156:159], v[124:127], 0
	v_add_f32_e32 v64, v48, v49
	v_add_f32_e32 v64, v50, v64
	v_add_f32_e32 v64, v51, v64
	v_add_f32_e32 v64, v52, v64
	v_add_f32_e32 v64, v53, v64
	v_cvt_pk_bf16_f32 v116, v48, v49
	v_cvt_pk_bf16_f32 v117, v50, v51
	ds_read_b64_tr_b16 v[156:157], v164 offset:28672
	ds_read_b64_tr_b16 v[158:159], v164 offset:29184
	v_add_f32_e32 v48, v54, v64
	s_waitcnt lgkmcnt(10)
	v_mfma_f32_32x32x16_bf16 v[64:79], v[148:151], v[124:127], 0
	v_add_f32_e32 v48, v55, v48
	v_add_f32_e32 v48, v56, v48
	v_add_f32_e32 v96, v57, v48
	v_cvt_pk_bf16_f32 v118, v52, v53
	v_cvt_pk_bf16_f32 v119, v54, v55
	ds_read_b64_tr_b16 v[48:49], v164 offset:25600
	ds_read_b64_tr_b16 v[50:51], v164 offset:26112
	s_waitcnt lgkmcnt(11)
	v_mfma_f32_32x32x16_bf16 v[80:95], v[152:155], v[120:123], v[80:95]
	v_add_f32_e32 v52, v58, v96
	v_add_f32_e32 v52, v59, v52
	v_add_f32_e32 v52, v60, v52
	v_add_f32_e32 v96, v61, v52
	v_cvt_pk_bf16_f32 v108, v56, v57
	v_cvt_pk_bf16_f32 v109, v58, v59
	ds_read_b64_tr_b16 v[52:53], v164 offset:29696
	ds_read_b64_tr_b16 v[54:55], v164 offset:30208
	s_waitcnt lgkmcnt(12)
	v_mfma_f32_32x32x16_bf16 v[64:79], v[144:147], v[120:123], v[64:79]
	v_add_f32_e32 v56, v62, v96
	v_add_f32_e32 v56, v63, v56
	v_add_f32_e32 v56, v32, v56
	v_add_f32_e32 v96, v33, v56
	v_cvt_pk_bf16_f32 v110, v60, v61
	v_cvt_pk_bf16_f32 v111, v62, v63
	ds_read_b64_tr_b16 v[56:57], v164 offset:26624
	ds_read_b64_tr_b16 v[58:59], v164 offset:27136
	s_waitcnt lgkmcnt(13)
	v_mfma_f32_32x32x16_bf16 v[80:95], v[140:143], v[112:115], v[80:95]
	v_add_f32_e32 v60, v34, v96
	v_add_f32_e32 v60, v35, v60
	v_add_f32_e32 v60, v36, v60
	v_add_f32_e32 v60, v37, v60
	v_cvt_pk_bf16_f32 v100, v32, v33
	v_cvt_pk_bf16_f32 v101, v34, v35
	ds_read_b64_tr_b16 v[32:33], v164 offset:30720
	ds_read_b64_tr_b16 v[34:35], v164 offset:31232
	s_waitcnt lgkmcnt(14)
	v_mfma_f32_32x32x16_bf16 v[64:79], v[136:139], v[112:115], v[64:79]
	v_add_f32_e32 v60, v38, v60
	v_add_f32_e32 v60, v39, v60
	v_add_f32_e32 v60, v40, v60
	v_add_f32_e32 v60, v41, v60
	v_cvt_pk_bf16_f32 v102, v36, v37
	v_cvt_pk_bf16_f32 v103, v38, v39
	ds_read_b64_tr_b16 v[36:37], v164 offset:27648
	ds_read_b64_tr_b16 v[38:39], v164 offset:28160
	s_waitcnt lgkmcnt(14)
	v_mfma_f32_32x32x16_bf16 v[80:95], v[132:135], v[104:107], v[80:95]
	v_add_f32_e32 v60, v42, v60
	v_add_f32_e32 v60, v43, v60
	v_add_f32_e32 v60, v44, v60
	v_add_f32_e32 v60, v45, v60
	v_cvt_pk_bf16_f32 v96, v40, v41
	v_cvt_pk_bf16_f32 v97, v42, v43
	ds_read_b64_tr_b16 v[40:41], v164 offset:31744
	ds_read_b64_tr_b16 v[42:43], v164 offset:32256
	v_mfma_f32_32x32x16_bf16 v[64:79], v[128:131], v[104:107], v[64:79]
	v_add_f32_e32 v60, v46, v60
	v_add_f32_e32 v60, v47, v60
	v_add_f32_e32 v191, 0, v60
	v_cvt_pk_bf16_f32 v98, v44, v45
	v_cvt_pk_bf16_f32 v99, v46, v47
	v_add_u32_e32 v203, s76, v184
	s_sub_i32 s0, s76, 64
	v_add_u32_e32 v149, 0xffffff81, v203
	s_cmp_le_i32 s0, s23
	v_sub_u32_e32 v150, v203, v186
	v_sub_u32_e32 v148, v203, v187
	v_subrev_u32_e32 v150, 68, v150
	v_subrev_u32_e32 v148, 68, v148
	s_cbranch_scc1 .LBB0_641
	v_cmp_le_i32_e64 s[0:1], v150, 27
	v_cmp_le_i32_e64 s[38:39], v150, 26
	v_cmp_le_i32_e64 s[40:41], v150, 25
	v_cmp_le_i32_e64 s[42:43], v150, 24
	v_cmp_le_i32_e64 s[44:45], v150, 19
	v_cmp_le_i32_e64 s[46:47], v150, 18
	v_cmp_le_i32_e64 s[50:51], v150, 17
	v_cmp_le_i32_e64 s[52:53], v150, 16
	v_cmp_le_i32_e64 s[54:55], v150, 11
	v_cmp_le_i32_e64 s[56:57], v150, 10
	v_cmp_le_i32_e64 s[58:59], v150, 9
	v_cmp_le_i32_e64 s[60:61], v150, 8
	v_cmp_le_i32_e64 s[62:63], v150, 3
	v_cmp_le_i32_e64 s[64:65], v150, 2
	v_cmp_le_i32_e64 s[66:67], v150, 1
	v_cmp_le_i32_e32 vcc, v149, v186
	v_cndmask_b32_e64 v64, v240, v64, s[0:1]
	v_cmp_lt_i32_e64 s[0:1], v149, v186
	v_cndmask_b32_e64 v65, v240, v65, s[38:39]
	v_cmp_le_i32_e64 s[38:39], v150, 57
	v_cndmask_b32_e64 v66, v240, v66, s[40:41]
	v_cmp_le_i32_e64 s[40:41], v150, 56
	v_cndmask_b32_e64 v67, v240, v67, s[42:43]
	v_cmp_le_i32_e64 s[42:43], v150, 51
	v_cndmask_b32_e64 v68, v240, v68, s[44:45]
	v_cmp_le_i32_e64 s[44:45], v150, 50
	v_cndmask_b32_e64 v69, v240, v69, s[46:47]
	v_cmp_le_i32_e64 s[46:47], v150, 49
	v_cndmask_b32_e64 v70, v240, v70, s[50:51]
	v_cmp_le_i32_e64 s[50:51], v150, 48
	v_cndmask_b32_e64 v71, v240, v71, s[52:53]
	v_cmp_le_i32_e64 s[52:53], v150, 43
	v_cndmask_b32_e64 v72, v240, v72, s[54:55]
	v_cmp_le_i32_e64 s[54:55], v150, 42
	v_cndmask_b32_e64 v73, v240, v73, s[56:57]
	v_cmp_le_i32_e64 s[56:57], v150, 41
	v_cndmask_b32_e64 v74, v240, v74, s[58:59]
	v_cmp_le_i32_e64 s[58:59], v150, 40
	v_cndmask_b32_e64 v75, v240, v75, s[60:61]
	v_cmp_le_i32_e64 s[60:61], v150, 35
	v_cndmask_b32_e64 v76, v240, v76, s[62:63]
	v_cmp_le_i32_e64 s[62:63], v150, 34
	v_cndmask_b32_e64 v77, v240, v77, s[64:65]
	v_cmp_le_i32_e64 s[64:65], v150, 33
	v_cndmask_b32_e64 v78, v240, v78, s[66:67]
	v_cmp_le_i32_e64 s[66:67], v150, 32
	v_cmp_gt_i32_e64 s[68:69], v150, 0
	s_and_saveexec_b64 s[28:29], s[68:69]
	s_mov_b32 s68, 0xff800000
	v_mov_b32_e32 v79, s68
	s_or_b64 exec, exec, s[28:29]
	v_cndmask_b32_e64 v81, v240, v81, s[0:1]
	v_cndmask_b32_e32 v80, v240, v80, vcc
	v_cndmask_b32_e64 v82, v240, v82, s[38:39]
	v_cndmask_b32_e64 v83, v240, v83, s[40:41]
	v_cndmask_b32_e64 v84, v240, v84, s[42:43]
	v_cndmask_b32_e64 v85, v240, v85, s[44:45]
	v_cndmask_b32_e64 v86, v240, v86, s[46:47]
	v_cndmask_b32_e64 v87, v240, v87, s[50:51]
	v_cndmask_b32_e64 v88, v240, v88, s[52:53]
	v_cndmask_b32_e64 v89, v240, v89, s[54:55]
	v_cndmask_b32_e64 v90, v240, v90, s[56:57]
	v_cndmask_b32_e64 v91, v240, v91, s[58:59]
	v_cndmask_b32_e64 v92, v240, v92, s[60:61]
	v_cndmask_b32_e64 v93, v240, v93, s[62:63]
	v_cndmask_b32_e64 v94, v240, v94, s[64:65]
	v_cndmask_b32_e64 v95, v240, v95, s[66:67]
.LBB0_641:
	s_add_i32 s0, s76, 0xffffff81
	s_cmp_ge_i32 s0, s78
	s_cbranch_scc1 .LBB0_645
	v_cmp_ge_i32_e32 vcc, v149, v187
	v_cmp_ge_i32_e64 s[0:1], v148, 27
	v_cmp_ge_i32_e64 s[38:39], v148, 26
	v_cmp_ge_i32_e64 s[40:41], v148, 25
	v_cmp_ge_i32_e64 s[42:43], v148, 24
	v_cmp_ge_i32_e64 s[44:45], v148, 19
	v_cmp_ge_i32_e64 s[46:47], v148, 18
	v_cmp_ge_i32_e64 s[50:51], v148, 17
	v_cmp_ge_i32_e64 s[52:53], v148, 16
	v_cmp_ge_i32_e64 s[54:55], v148, 11
	v_cmp_ge_i32_e64 s[56:57], v148, 10
	v_cmp_ge_i32_e64 s[58:59], v148, 9
	v_cmp_ge_i32_e64 s[60:61], v148, 8
	v_cmp_ge_i32_e64 s[62:63], v148, 3
	v_cmp_ge_i32_e64 s[64:65], v148, 2
	v_cmp_ge_i32_e64 s[66:67], v148, 1
	v_cndmask_b32_e64 v64, v240, v64, s[0:1]
	v_cmp_ge_i32_e64 s[0:1], v148, 58
	v_cndmask_b32_e64 v65, v240, v65, s[38:39]
	v_cmp_ge_i32_e64 s[38:39], v148, 57
	v_cndmask_b32_e64 v66, v240, v66, s[40:41]
	v_cmp_ge_i32_e64 s[40:41], v148, 56
	v_cndmask_b32_e64 v67, v240, v67, s[42:43]
	v_cmp_ge_i32_e64 s[42:43], v148, 51
	v_cndmask_b32_e64 v68, v240, v68, s[44:45]
	v_cmp_ge_i32_e64 s[44:45], v148, 50
	v_cndmask_b32_e64 v69, v240, v69, s[46:47]
	v_cmp_ge_i32_e64 s[46:47], v148, 49
	v_cndmask_b32_e64 v70, v240, v70, s[50:51]
	v_cmp_ge_i32_e64 s[50:51], v148, 48
	v_cndmask_b32_e64 v71, v240, v71, s[52:53]
	v_cmp_ge_i32_e64 s[52:53], v148, 43
	v_cndmask_b32_e64 v72, v240, v72, s[54:55]
	v_cmp_ge_i32_e64 s[54:55], v148, 42
	v_cndmask_b32_e64 v73, v240, v73, s[56:57]
	v_cmp_ge_i32_e64 s[56:57], v148, 41
	v_cndmask_b32_e64 v74, v240, v74, s[58:59]
	v_cmp_ge_i32_e64 s[58:59], v148, 40
	v_cndmask_b32_e64 v75, v240, v75, s[60:61]
	v_cmp_ge_i32_e64 s[60:61], v148, 35
	v_cndmask_b32_e64 v76, v240, v76, s[62:63]
	v_cmp_ge_i32_e64 s[62:63], v148, 34
	v_cndmask_b32_e64 v77, v240, v77, s[64:65]
	v_cmp_ge_i32_e64 s[64:65], v148, 33
	v_cndmask_b32_e64 v78, v240, v78, s[66:67]
	v_cmp_ge_i32_e64 s[66:67], v148, 32
	v_cmp_lt_i32_e64 s[68:69], v148, 0
	s_and_saveexec_b64 s[28:29], s[68:69]
	s_mov_b32 s68, 0xff800000
	v_mov_b32_e32 v79, s68
	s_or_b64 exec, exec, s[28:29]
	v_cndmask_b32_e32 v80, v240, v80, vcc
	v_cndmask_b32_e64 v81, v240, v81, s[0:1]
	v_cndmask_b32_e64 v82, v240, v82, s[38:39]
	v_cndmask_b32_e64 v83, v240, v83, s[40:41]
	v_cndmask_b32_e64 v84, v240, v84, s[42:43]
	v_cndmask_b32_e64 v85, v240, v85, s[44:45]
	v_cndmask_b32_e64 v86, v240, v86, s[46:47]
	v_cndmask_b32_e64 v87, v240, v87, s[50:51]
	v_cndmask_b32_e64 v88, v240, v88, s[52:53]
	v_cndmask_b32_e64 v89, v240, v89, s[54:55]
	v_cndmask_b32_e64 v90, v240, v90, s[56:57]
	v_cndmask_b32_e64 v91, v240, v91, s[58:59]
	v_cndmask_b32_e64 v92, v240, v92, s[60:61]
	v_cndmask_b32_e64 v93, v240, v93, s[62:63]
	v_cndmask_b32_e64 v94, v240, v94, s[64:65]
	v_cndmask_b32_e64 v95, v240, v95, s[66:67]

.LBB0_657:
	s_sub_i32 s0, s23, 0x80
	s_max_i32 s0, s0, 0
	s_add_i32 s1, s76, 1
	s_cmp_le_i32 s1, s0
	s_cbranch_scc1 .Lxb_idle
	s_sub_i32 s1, s76, 0x9e
	s_cmp_gt_i32 s1, s23
	s_cbranch_scc1 .Lxb_idle
	v_add_u32_e32 v194, s72, v190
	ds_read_b64_tr_b16 v[168:169], v194 offset:24576
	ds_read_b64_tr_b16 v[170:171], v194 offset:25088
	s_waitcnt lgkmcnt(9)
	v_mfma_f32_32x32x16_bf16 v[48:63], v[156:159], v[124:127], 0
	v_add_f32_e32 v32, v80, v81
	v_add_f32_e32 v32, v82, v32
	v_add_f32_e32 v32, v83, v32
	v_add_f32_e32 v32, v84, v32
	v_add_f32_e32 v32, v85, v32
	v_cvt_pk_bf16_f32 v116, v80, v81
	v_cvt_pk_bf16_f32 v117, v82, v83
	ds_read_b64_tr_b16 v[164:165], v194 offset:28672
	ds_read_b64_tr_b16 v[166:167], v194 offset:29184
	v_add_f32_e32 v32, v86, v32
	v_add_f32_e32 v32, v87, v32
	v_add_f32_e32 v32, v88, v32
	v_add_f32_e32 v80, v89, v32
	s_waitcnt lgkmcnt(10)
	v_mfma_f32_32x32x16_bf16 v[32:47], v[148:151], v[124:127], 0
	v_cvt_pk_bf16_f32 v118, v84, v85
	v_cvt_pk_bf16_f32 v119, v86, v87
	ds_read_b64_tr_b16 v[160:161], v194 offset:25600
	ds_read_b64_tr_b16 v[162:163], v194 offset:26112
	s_waitcnt lgkmcnt(11)
	v_mfma_f32_32x32x16_bf16 v[48:63], v[152:155], v[120:123], v[48:63]
	v_add_f32_e32 v80, v90, v80
	v_add_f32_e32 v80, v91, v80
	v_add_f32_e32 v80, v92, v80
	v_add_f32_e32 v80, v93, v80
	v_cvt_pk_bf16_f32 v108, v88, v89
	v_cvt_pk_bf16_f32 v109, v90, v91
	ds_read_b64_tr_b16 v[88:89], v194 offset:29696
	ds_read_b64_tr_b16 v[90:91], v194 offset:30208
	s_waitcnt lgkmcnt(12)
	v_mfma_f32_32x32x16_bf16 v[32:47], v[144:147], v[120:123], v[32:47]
	v_add_f32_e32 v80, v94, v80
	v_add_f32_e32 v80, v95, v80
	v_add_f32_e32 v80, v64, v80
	v_add_f32_e32 v80, v65, v80
	v_cvt_pk_bf16_f32 v110, v92, v93
	v_cvt_pk_bf16_f32 v111, v94, v95
	ds_read_b64_tr_b16 v[84:85], v194 offset:26624
	ds_read_b64_tr_b16 v[86:87], v194 offset:27136
	s_waitcnt lgkmcnt(13)
	v_mfma_f32_32x32x16_bf16 v[48:63], v[140:143], v[112:115], v[48:63]
	v_add_f32_e32 v80, v66, v80
	v_add_f32_e32 v80, v67, v80
	v_add_f32_e32 v80, v68, v80
	v_add_f32_e32 v92, v69, v80
	v_cvt_pk_bf16_f32 v100, v64, v65
	v_cvt_pk_bf16_f32 v101, v66, v67
	ds_read_b64_tr_b16 v[80:81], v194 offset:30720
	ds_read_b64_tr_b16 v[82:83], v194 offset:31232
	s_waitcnt lgkmcnt(14)
	v_mfma_f32_32x32x16_bf16 v[32:47], v[136:139], v[112:115], v[32:47]
	v_add_f32_e32 v64, v70, v92
	v_add_f32_e32 v64, v71, v64
	v_add_f32_e32 v64, v72, v64
	v_add_f32_e32 v64, v73, v64
	v_cvt_pk_bf16_f32 v102, v68, v69
	v_cvt_pk_bf16_f32 v103, v70, v71
	ds_read_b64_tr_b16 v[68:69], v194 offset:27648
	ds_read_b64_tr_b16 v[70:71], v194 offset:28160
	s_waitcnt lgkmcnt(14)
	v_mfma_f32_32x32x16_bf16 v[48:63], v[132:135], v[104:107], v[48:63]
	v_add_f32_e32 v64, v74, v64
	v_add_f32_e32 v64, v75, v64
	v_add_f32_e32 v64, v76, v64
	v_add_f32_e32 v92, v77, v64
	v_cvt_pk_bf16_f32 v96, v72, v73
	v_cvt_pk_bf16_f32 v97, v74, v75
	ds_read_b64_tr_b16 v[64:65], v194 offset:31744
	ds_read_b64_tr_b16 v[66:67], v194 offset:32256
	v_mfma_f32_32x32x16_bf16 v[32:47], v[128:131], v[104:107], v[32:47]
	v_add_f32_e32 v72, v78, v92
	v_add_f32_e32 v72, v79, v72
	v_add_f32_e32 v72, 0, v72
	v_cvt_pk_bf16_f32 v98, v76, v77
	v_cvt_pk_bf16_f32 v99, v78, v79
	v_sub_u32_e32 v222, v203, v186
	v_sub_u32_e32 v223, v203, v187
	v_subrev_u32_e32 v222, 4, v222
	v_subrev_u32_e32 v223, 4, v223
	s_cmp_le_i32 s76, s23
	s_cbranch_scc1 .LBB0_661
	v_cmp_le_i32_e64 s[0:1], v222, 27
	v_cmp_le_i32_e64 s[38:39], v222, 26
	v_cmp_le_i32_e64 s[40:41], v222, 25
	v_cmp_le_i32_e64 s[42:43], v222, 24
	v_cmp_le_i32_e64 s[44:45], v222, 19
	v_cmp_le_i32_e64 s[46:47], v222, 18
	v_cmp_le_i32_e64 s[50:51], v222, 17
	v_cmp_le_i32_e64 s[52:53], v222, 16
	v_cmp_le_i32_e64 s[54:55], v222, 11
	v_cmp_le_i32_e64 s[56:57], v222, 10
	v_cmp_le_i32_e64 s[58:59], v222, 9
	v_cmp_le_i32_e64 s[60:61], v222, 8
	v_cmp_le_i32_e64 s[62:63], v222, 3
	v_cmp_le_i32_e64 s[64:65], v222, 2
	v_cmp_le_i32_e64 s[66:67], v222, 1
	v_cmp_ge_i32_e32 vcc, 59, v222
	v_cndmask_b32_e64 v32, v240, v32, s[0:1]
	v_cmp_lt_i32_e64 s[0:1], v222, 59
	v_cndmask_b32_e64 v33, v240, v33, s[38:39]
	v_cmp_le_i32_e64 s[38:39], v222, 57
	v_cndmask_b32_e64 v34, v240, v34, s[40:41]
	v_cmp_le_i32_e64 s[40:41], v222, 56
	v_cndmask_b32_e64 v35, v240, v35, s[42:43]
	v_cmp_le_i32_e64 s[42:43], v222, 51
	v_cndmask_b32_e64 v36, v240, v36, s[44:45]
	v_cmp_le_i32_e64 s[44:45], v222, 50
	v_cndmask_b32_e64 v37, v240, v37, s[46:47]
	v_cmp_le_i32_e64 s[46:47], v222, 49
	v_cndmask_b32_e64 v38, v240, v38, s[50:51]
	v_cmp_le_i32_e64 s[50:51], v222, 48
	v_cndmask_b32_e64 v39, v240, v39, s[52:53]
	v_cmp_le_i32_e64 s[52:53], v222, 43
	v_cndmask_b32_e64 v40, v240, v40, s[54:55]
	v_cmp_le_i32_e64 s[54:55], v222, 42
	v_cndmask_b32_e64 v41, v240, v41, s[56:57]
	v_cmp_le_i32_e64 s[56:57], v222, 41
	v_cndmask_b32_e64 v42, v240, v42, s[58:59]
	v_cmp_le_i32_e64 s[58:59], v222, 40
	v_cndmask_b32_e64 v43, v240, v43, s[60:61]
	v_cmp_le_i32_e64 s[60:61], v222, 35
	v_cndmask_b32_e64 v44, v240, v44, s[62:63]
	v_cmp_le_i32_e64 s[62:63], v222, 34
	v_cndmask_b32_e64 v45, v240, v45, s[64:65]
	v_cmp_le_i32_e64 s[64:65], v222, 33
	v_cndmask_b32_e64 v46, v240, v46, s[66:67]
	v_cmp_le_i32_e64 s[66:67], v222, 32
	v_cmp_gt_i32_e64 s[68:69], v222, 0
	s_and_saveexec_b64 s[72:73], s[68:69]
	s_mov_b32 s68, 0xff800000
	v_mov_b32_e32 v47, s68
	s_or_b64 exec, exec, s[72:73]
	v_cndmask_b32_e64 v49, v240, v49, s[0:1]
	v_cndmask_b32_e32 v48, v240, v48, vcc
	v_cndmask_b32_e64 v50, v240, v50, s[38:39]
	v_cndmask_b32_e64 v51, v240, v51, s[40:41]
	v_cndmask_b32_e64 v52, v240, v52, s[42:43]
	v_cndmask_b32_e64 v53, v240, v53, s[44:45]
	v_cndmask_b32_e64 v54, v240, v54, s[46:47]
	v_cndmask_b32_e64 v55, v240, v55, s[50:51]
	v_cndmask_b32_e64 v56, v240, v56, s[52:53]
	v_cndmask_b32_e64 v57, v240, v57, s[54:55]
	v_cndmask_b32_e64 v58, v240, v58, s[56:57]
	v_cndmask_b32_e64 v59, v240, v59, s[58:59]
	v_cndmask_b32_e64 v60, v240, v60, s[60:61]
	v_cndmask_b32_e64 v61, v240, v61, s[62:63]
	v_cndmask_b32_e64 v62, v240, v62, s[64:65]
	v_cndmask_b32_e64 v63, v240, v63, s[66:67]
.LBB0_661:
	s_sub_i32 s0, s76, 63
	s_cmp_ge_i32 s0, s78
	s_cbranch_scc1 .LBB0_665
	v_cmp_ge_i32_e64 s[0:1], v223, 27
	v_cmp_ge_i32_e64 s[38:39], v223, 26
	v_cmp_ge_i32_e64 s[40:41], v223, 25
	v_cmp_ge_i32_e64 s[42:43], v223, 24
	v_cmp_ge_i32_e64 s[44:45], v223, 19
	v_cmp_ge_i32_e64 s[46:47], v223, 18
	v_cmp_ge_i32_e64 s[50:51], v223, 17
	v_cmp_ge_i32_e64 s[52:53], v223, 16
	v_cmp_ge_i32_e64 s[54:55], v223, 11
	v_cmp_ge_i32_e64 s[56:57], v223, 10
	v_cmp_ge_i32_e64 s[58:59], v223, 9
	v_cmp_ge_i32_e64 s[60:61], v223, 8
	v_cmp_ge_i32_e64 s[62:63], v223, 3
	v_cmp_ge_i32_e64 s[64:65], v223, 2
	v_cmp_ge_i32_e64 s[66:67], v223, 1
	v_cmp_le_i32_e32 vcc, 59, v223
	v_cndmask_b32_e64 v32, v240, v32, s[0:1]
	v_cmp_ge_i32_e64 s[0:1], v223, 58
	v_cndmask_b32_e64 v33, v240, v33, s[38:39]
	v_cmp_ge_i32_e64 s[38:39], v223, 57
	v_cndmask_b32_e64 v34, v240, v34, s[40:41]
	v_cmp_ge_i32_e64 s[40:41], v223, 56
	v_cndmask_b32_e64 v35, v240, v35, s[42:43]
	v_cmp_ge_i32_e64 s[42:43], v223, 51
	v_cndmask_b32_e64 v36, v240, v36, s[44:45]
	v_cmp_ge_i32_e64 s[44:45], v223, 50
	v_cndmask_b32_e64 v37, v240, v37, s[46:47]
	v_cmp_ge_i32_e64 s[46:47], v223, 49
	v_cndmask_b32_e64 v38, v240, v38, s[50:51]
	v_cmp_ge_i32_e64 s[50:51], v223, 48
	v_cndmask_b32_e64 v39, v240, v39, s[52:53]
	v_cmp_ge_i32_e64 s[52:53], v223, 43
	v_cndmask_b32_e64 v40, v240, v40, s[54:55]
	v_cmp_ge_i32_e64 s[54:55], v223, 42
	v_cndmask_b32_e64 v41, v240, v41, s[56:57]
	v_cmp_ge_i32_e64 s[56:57], v223, 41
	v_cndmask_b32_e64 v42, v240, v42, s[58:59]
	v_cmp_ge_i32_e64 s[58:59], v223, 40
	v_cndmask_b32_e64 v43, v240, v43, s[60:61]
	v_cmp_ge_i32_e64 s[60:61], v223, 35
	v_cndmask_b32_e64 v44, v240, v44, s[62:63]
	v_cmp_ge_i32_e64 s[62:63], v223, 34
	v_cndmask_b32_e64 v45, v240, v45, s[64:65]
	v_cmp_ge_i32_e64 s[64:65], v223, 33
	v_cndmask_b32_e64 v46, v240, v46, s[66:67]
	v_cmp_ge_i32_e64 s[66:67], v223, 32
	v_cmp_lt_i32_e64 s[68:69], v223, 0
	s_and_saveexec_b64 s[72:73], s[68:69]
	s_mov_b32 s68, 0xff800000
	v_mov_b32_e32 v47, s68
	s_or_b64 exec, exec, s[72:73]
	v_cndmask_b32_e32 v48, v240, v48, vcc
	v_cndmask_b32_e64 v49, v240, v49, s[0:1]
	v_cndmask_b32_e64 v50, v240, v50, s[38:39]
	v_cndmask_b32_e64 v51, v240, v51, s[40:41]
	v_cndmask_b32_e64 v52, v240, v52, s[42:43]
	v_cndmask_b32_e64 v53, v240, v53, s[44:45]
	v_cndmask_b32_e64 v54, v240, v54, s[46:47]
	v_cndmask_b32_e64 v55, v240, v55, s[50:51]
	v_cndmask_b32_e64 v56, v240, v56, s[52:53]
	v_cndmask_b32_e64 v57, v240, v57, s[54:55]
	v_cndmask_b32_e64 v58, v240, v58, s[56:57]
	v_cndmask_b32_e64 v59, v240, v59, s[58:59]
	v_cndmask_b32_e64 v60, v240, v60, s[60:61]
	v_cndmask_b32_e64 v61, v240, v61, s[62:63]
	v_cndmask_b32_e64 v62, v240, v62, s[64:65]
	v_cndmask_b32_e64 v63, v240, v63, s[66:67]
